# baseline (speedup 1.0000x reference)
; __device__ __forceinline__ int opaque_tid() { int t = threadIdx.x; asm volatile("" : "+v"(t)); return t; }
; __device__ void phase_norm(const Params& p, int src_is_input, const bf16_t* delta, const float* gain, int final_out, int dry) {
;   unsigned char* ws = p.ws;
;   const int tid = opaque_tid();
;   const int lane = tid & 63, wid = tid >> 6;
;   bf16_t* xb = (bf16_t*)(ws + O_XB);
;   float* rstd = (float*)(ws + O_RSTD);
;   const int stride = gridDim.x * 8;
;   int row = blockIdx.x * 8 + wid;
;   uint4 dn[2], xn[2];
;     ...
;   if (row < T_TOK) NORM_FETCH(row);
;   float gq[16];
; #pragma unroll
;   for (int i = 0; i < 2; ++i) {
;     const float4 a = *(const float4*)(gain + i * 512 + lane * 8), b = *(const float4*)(gain + i * 512 + lane * 8 + 4);
;     gq[i * 8 + 0] = a.x; gq[i * 8 + 1] = a.y; gq[i * 8 + 2] = a.z; gq[i * 8 + 3] = a.w;
;     gq[i * 8 + 4] = b.x; gq[i * 8 + 5] = b.y; gq[i * 8 + 6] = b.z; gq[i * 8 + 7] = b.w;
;   }
;   while (row < T_TOK) {
.LBB0_1283:
	s_or_b64 exec, exec, s[4:5]
	s_add_i32 s28, s28, 1
	s_and_saveexec_b64 s[20:21], vcc
	s_cbranch_execz .LBB0_1280
	v_lshlrev_b64 v[20:21], 2, v[0:1]
	v_lshl_add_u64 v[14:15], s[2:3], 0, v[20:21]
	global_load_dwordx4 v[2:5], v[14:15], off offset:16
	global_load_dwordx4 v[6:9], v[14:15], off
	global_load_dwordx4 v[10:13], v[14:15], off offset:2064
	s_nop 0
	global_load_dwordx4 v[14:17], v[14:15], off offset:2048
	v_and_b32_e32 v22, 64, v228
	v_add_u32_e32 v22, 64, v22
	v_xor_b32_e32 v23, 32, v228
	v_cmp_lt_i32_e32 vcc, v23, v22
	v_readlane_b32 s6, v254, 10
	v_cmp_eq_u32_e64 s[4:5], 0, v19
	v_cndmask_b32_e32 v23, v228, v23, vcc
	v_lshlrev_b32_e32 v66, 2, v23
	v_xor_b32_e32 v23, 16, v228
	v_cmp_lt_i32_e32 vcc, v23, v22
	v_add_u32_e32 v18, s6, v18
	v_ashrrev_i32_e32 v19, 31, v18
	v_cndmask_b32_e32 v23, v228, v23, vcc
	v_lshlrev_b32_e32 v67, 2, v23
	v_xor_b32_e32 v23, 8, v228
	v_cmp_lt_i32_e32 vcc, v23, v22
	s_cmp_ge_u32 s28, s29
	v_lshlrev_b64 v[18:19], 11, v[18:19]
	v_cndmask_b32_e32 v23, v228, v23, vcc
	v_lshlrev_b32_e32 v68, 2, v23
	v_xor_b32_e32 v23, 4, v228
	v_cmp_lt_i32_e32 vcc, v23, v22
	s_cselect_b64 s[22:23], -1, 0
	v_lshlrev_b64 v[52:53], 1, v[0:1]
	v_cndmask_b32_e32 v23, v228, v23, vcc
	v_lshlrev_b32_e32 v69, 2, v23
	v_xor_b32_e32 v23, 2, v228
	v_cmp_lt_i32_e32 vcc, v23, v22
	s_waitcnt vmcnt(7)
	v_lshl_add_u64 v[56:57], s[14:15], 0, v[18:19]
	v_lshl_add_u64 v[60:61], s[8:9], 0, v[18:19]
	v_cndmask_b32_e32 v23, v228, v23, vcc
	v_lshlrev_b32_e32 v70, 2, v23
	v_xor_b32_e32 v23, 1, v228
	v_cmp_lt_i32_e32 vcc, v23, v22
	v_lshl_add_u64 v[62:63], v[50:51], 2, s[18:19]
	s_mov_b64 s[24:25], 0
	v_cndmask_b32_e32 v22, v228, v23, vcc
	v_lshlrev_b32_e32 v71, 2, v22
	v_lshlrev_b64 v[22:23], 11, v[50:51]
	v_lshl_add_u64 v[54:55], s[14:15], 0, v[22:23]
	v_lshlrev_b64 v[22:23], 12, v[50:51]
	v_lshl_add_u64 v[20:21], v[22:23], 0, v[20:21]
	v_lshl_add_u64 v[58:59], s[16:17], 0, v[20:21]
	s_waitcnt vmcnt(0)
	v_readlane_b32 s6, v254, 19
	s_nop 1
	v_add_u32_e32 v50, s6, v50
	s_mov_b32 s6, 0x10000
	v_cmp_gt_i32_e32 vcc, s6, v50
	s_and_saveexec_b64 s[26:27], vcc
	s_cbranch_execz .Lnrm_pre_skip
	v_lshl_add_u64 v[18:19], v[56:57], 0, v[52:53]
	v_add_co_u32_e32 v30, vcc, 0x61a6000, v18
	v_lshl_add_u64 v[22:23], v[60:61], 0, v[52:53]
	s_nop 0
	v_addc_co_u32_e32 v31, vcc, 0, v19, vcc
	global_load_dwordx4 v[18:21], v[22:23], off
	s_nop 0
	global_load_dwordx4 v[22:25], v[22:23], off offset:1024
	s_nop 0
	global_load_dwordx4 v[26:29], v[30:31], off
	s_nop 0
	global_load_dwordx4 v[30:33], v[30:31], off offset:1024
.Lnrm_pre_skip:
	s_or_b64 exec, exec, s[26:27]
	v_readlane_b32 s6, v254, 15
	v_readlane_b32 s7, v254, 16
	s_nop 0
	v_lshl_add_u64 v[56:57], v[56:57], 0, s[6:7]
	v_lshl_add_u64 v[60:61], v[60:61], 0, s[6:7]
	s_branch .LBB0_1287

; __device__ __forceinline__ float lo2f(unsigned u) { return __uint_as_float(u << 16); }
; __device__ __forceinline__ float hi2f(unsigned u) { return __uint_as_float(u & 0xffff0000u); }
; __device__ void phase_norm(const Params& p, int src_is_input, const bf16_t* delta, const float* gain, int final_out, int dry) {
;     ...
;   while (row < T_TOK) {
;     float dv[16], xv[16];
;     float ss = 0.f;
; #pragma unroll
;     for (int i = 0; i < 2; ++i) {
;       const unsigned du[4] = {dn[i].x, dn[i].y, dn[i].z, dn[i].w}, xu[4] = {xn[i].x, xn[i].y, xn[i].z, xn[i].w};
; #pragma unroll
;       for (int j = 0; j < 4; ++j) {
;         dv[i * 8 + 2 * j] = lo2f(du[j]); dv[i * 8 + 2 * j + 1] = hi2f(du[j]);
;         xv[i * 8 + 2 * j] = lo2f(xu[j]); xv[i * 8 + 2 * j + 1] = hi2f(xu[j]);
;       }
;     }
; #pragma unroll
;     for (int j = 0; j < 16; ++j) ss += dv[j] * dv[j];
;     const int nrow = row + stride;
;     if (nrow < T_TOK) NORM_FETCH(nrow);
;     ss = wave_sum(ss);
;     const float rr = rsqrtf(ss * (1.f / 1024.f) + 1e-6f);
;     float y[16];
;     float ss2 = 0.f;
; #pragma unroll
;     for (int j = 0; j < 16; ++j) { y[j] = xv[j] + dv[j] * rr * gq[j]; ss2 += y[j] * y[j]; }
;     if (!dry) {
; #pragma unroll
;       for (int i = 0; i < 2; ++i) {
;         if (final_out) {
;           float* op = p.out + (size_t)row * DM + i * 512 + lane * 8;
;           *(float4*)op = make_float4(y[i * 8 + 0], y[i * 8 + 1], y[i * 8 + 2], y[i * 8 + 3]);
;           *(float4*)(op + 4) = make_float4(y[i * 8 + 4], y[i * 8 + 5], y[i * 8 + 6], y[i * 8 + 7]);
;         } else {
;           uint4 o;
;           o.x = pack2(y[i * 8 + 0], y[i * 8 + 1]); o.y = pack2(y[i * 8 + 2], y[i * 8 + 3]);
;           o.z = pack2(y[i * 8 + 4], y[i * 8 + 5]); o.w = pack2(y[i * 8 + 6], y[i * 8 + 7]);
;           *(uint4*)(xb + (size_t)row * DM + i * 512 + lane * 8) = o;
.LBB0_1286:
	s_and_b64 s[6:7], exec, s[6:7]
	s_or_b64 s[24:25], s[6:7], s[24:25]
	v_readlane_b32 s6, v254, 15
	v_readlane_b32 s7, v254, 16
	v_readlane_b32 s26, v254, 17
	v_readlane_b32 s27, v254, 18
	v_lshl_add_u64 v[54:55], v[54:55], 0, s[6:7]
	v_lshl_add_u64 v[56:57], v[56:57], 0, s[6:7]
	v_lshl_add_u64 v[60:61], v[60:61], 0, s[6:7]
	v_readlane_b32 s6, v254, 21
	v_readlane_b32 s7, v254, 22
	v_lshl_add_u64 v[58:59], v[58:59], 0, s[26:27]
	v_mov_b64_e32 v[38:39], v[26:27]
	v_lshl_add_u64 v[62:63], v[62:63], 0, s[6:7]
	v_mov_b64_e32 v[40:41], v[28:29]
	v_mov_b64_e32 v[34:35], v[30:31]
	v_mov_b64_e32 v[36:37], v[32:33]
	v_mov_b64_e32 v[46:47], v[18:19]
	v_mov_b64_e32 v[48:49], v[20:21]
	v_mov_b64_e32 v[42:43], v[22:23]
	v_mov_b64_e32 v[44:45], v[24:25]
	s_andn2_b64 exec, exec, s[24:25]
	s_cbranch_execz .LBB0_1280
	s_branch .Lnrm_top_y
.LBB0_1287:
	v_readlane_b32 s6, v254, 19
	v_cmp_lt_i32_e64 s[98:99], s65, v50
	s_nop 0
	v_add_u32_e32 v50, s6, v50
	s_mov_b32 s6, 0x10000
	v_cmp_gt_i32_e32 vcc, s6, v50
	s_mov_b64 s[6:7], s[98:99]
	s_and_saveexec_b64 s[26:27], vcc
	s_cbranch_execnz .Lnrm_ld
	s_waitcnt vmcnt(0)
	s_branch .LBB0_1289
.Lnrm_ld:
	v_lshl_add_u64 v[180:181], v[56:57], 0, v[52:53]
	v_add_co_u32_e32 v192, vcc, 0x61a6000, v180
	v_lshl_add_u64 v[184:185], v[60:61], 0, v[52:53]
	s_nop 0
	v_addc_co_u32_e32 v193, vcc, 0, v181, vcc
	global_load_dwordx4 v[180:183], v[184:185], off
	s_nop 0
	global_load_dwordx4 v[184:187], v[184:185], off offset:1024
	s_nop 0
	global_load_dwordx4 v[188:191], v[192:193], off
	s_nop 0
	global_load_dwordx4 v[192:195], v[192:193], off offset:1024
.LBB0_1289:
	s_or_b64 exec, exec, s[26:27]
	v_lshlrev_b32_e32 v64, 16, v46
	v_and_b32_e32 v65, 0xffff0000, v46
	v_lshlrev_b32_e32 v46, 16, v47
	v_and_b32_e32 v47, 0xffff0000, v47
	v_lshlrev_b32_e32 v74, 16, v42
	v_and_b32_e32 v75, 0xffff0000, v42
	v_lshlrev_b32_e32 v76, 16, v43
	v_and_b32_e32 v77, 0xffff0000, v43
	v_pk_mul_f32 v[42:43], v[64:65], v[64:65]
	v_lshlrev_b32_e32 v78, 16, v44
	v_and_b32_e32 v79, 0xffff0000, v44
	v_lshlrev_b32_e32 v80, 16, v45
	v_and_b32_e32 v81, 0xffff0000, v45
	v_pk_mul_f32 v[44:45], v[46:47], v[46:47]
	v_add_f32_e32 v0, v42, v43
	v_lshlrev_b32_e32 v72, 16, v48
	v_and_b32_e32 v73, 0xffff0000, v48
	v_add_f32_e32 v0, v0, v44
	v_pk_mul_f32 v[82:83], v[72:73], v[72:73]
	v_add_f32_e32 v0, v45, v0
	v_lshlrev_b32_e32 v48, 16, v49
	v_and_b32_e32 v49, 0xffff0000, v49
	v_add_f32_e32 v0, v82, v0
	v_pk_mul_f32 v[84:85], v[48:49], v[48:49]
	v_add_f32_e32 v0, v83, v0
	v_add_f32_e32 v0, v84, v0
	v_pk_mul_f32 v[86:87], v[74:75], v[74:75]
	v_add_f32_e32 v0, v85, v0
	v_add_f32_e32 v0, v86, v0
	v_pk_mul_f32 v[88:89], v[76:77], v[76:77]
	v_add_f32_e32 v0, v87, v0
	v_add_f32_e32 v0, v88, v0
	v_pk_mul_f32 v[90:91], v[78:79], v[78:79]
	v_add_f32_e32 v0, v89, v0
	v_add_f32_e32 v0, v90, v0
	v_pk_mul_f32 v[92:93], v[80:81], v[80:81]
	v_add_f32_e32 v0, v91, v0
	v_add_f32_e32 v0, v92, v0
	v_add_f32_e32 v0, v93, v0
	v_lshlrev_b32_e32 v82, 16, v34
	v_and_b32_e32 v83, 0xffff0000, v34
	v_lshlrev_b32_e32 v84, 16, v35
	v_and_b32_e32 v85, 0xffff0000, v35
	v_lshlrev_b32_e32 v86, 16, v36
	v_and_b32_e32 v87, 0xffff0000, v36
	v_lshlrev_b32_e32 v88, 16, v37
	v_and_b32_e32 v89, 0xffff0000, v37
	v_lshlrev_b32_e32 v42, 16, v38
	v_lshlrev_b32_e32 v44, 16, v40
	v_and_b32_e32 v43, 0xffff0000, v38
	v_lshlrev_b32_e32 v38, 16, v39
	v_and_b32_e32 v39, 0xffff0000, v39
	v_and_b32_e32 v45, 0xffff0000, v40
	v_lshlrev_b32_e32 v40, 16, v41
	v_and_b32_e32 v41, 0xffff0000, v41
	s_nop 1
	v_add_f32_dpp v0, v0, v0 quad_perm:[1,0,3,2] row_mask:0xf bank_mask:0xf
	s_nop 1
	v_add_f32_dpp v0, v0, v0 quad_perm:[2,3,0,1] row_mask:0xf bank_mask:0xf
	s_nop 1
	v_add_f32_dpp v0, v0, v0 row_ror:4 row_mask:0xf bank_mask:0xf
	s_nop 1
	v_add_f32_dpp v0, v0, v0 row_ror:8 row_mask:0xf bank_mask:0xf
	v_mov_b32_e32 v176, v0
	s_nop 1
	v_permlane16_swap_b32_e32 v0, v176
	s_nop 1
	v_add_f32_e32 v0, v0, v176
	v_mov_b32_e32 v176, v0
	s_nop 1
	v_permlane32_swap_b32_e32 v0, v176
	s_nop 1
	v_add_f32_e32 v0, v0, v176
	v_fmamk_f32 v0, v0, 0x3a800000, v216
	v_mul_f32_e32 v34, 0x4b800000, v0
	v_cmp_gt_f32_e32 vcc, s44, v0
	s_nop 1
	v_cndmask_b32_e32 v0, v0, v34, vcc
	v_rsq_f32_e32 v0, v0
	s_nop 0
	v_mul_f32_e32 v34, 0x45800000, v0
	v_cndmask_b32_e32 v0, v0, v34, vcc
	v_pk_mul_f32 v[34:35], v[0:1], v[64:65] op_sel_hi:[0,1]
	v_pk_mul_f32 v[36:37], v[0:1], v[46:47] op_sel_hi:[0,1]
	v_pk_fma_f32 v[34:35], v[6:7], v[34:35], v[42:43]
	v_pk_fma_f32 v[36:37], v[8:9], v[36:37], v[38:39]
	v_pk_mul_f32 v[38:39], v[0:1], v[72:73] op_sel_hi:[0,1]
	v_pk_mul_f32 v[42:43], v[0:1], v[48:49] op_sel_hi:[0,1]
	v_pk_fma_f32 v[38:39], v[2:3], v[38:39], v[44:45]
	v_pk_fma_f32 v[40:41], v[4:5], v[42:43], v[40:41]
	v_pk_mul_f32 v[42:43], v[0:1], v[74:75] op_sel_hi:[0,1]
	v_pk_mul_f32 v[44:45], v[0:1], v[76:77] op_sel_hi:[0,1]
	v_pk_mul_f32 v[46:47], v[0:1], v[78:79] op_sel_hi:[0,1]
	v_pk_mul_f32 v[48:49], v[0:1], v[80:81] op_sel_hi:[0,1]
	v_pk_fma_f32 v[42:43], v[14:15], v[42:43], v[82:83]
	v_pk_fma_f32 v[44:45], v[16:17], v[44:45], v[84:85]
	v_pk_fma_f32 v[46:47], v[10:11], v[46:47], v[86:87]
	s_waitcnt vmcnt(4)
	s_andn2_b64 vcc, exec, s[22:23]
	v_pk_fma_f32 v[48:49], v[12:13], v[48:49], v[88:89]
	s_cbranch_vccnz .LBB0_1298
	v_lshl_add_u64 v[64:65], v[54:55], 0, v[52:53]
	s_mov_b64 s[26:27], -1
	s_and_b64 vcc, exec, s[10:11]
	s_cbranch_vccz .LBB0_1294
	v_add_co_u32_e32 v76, vcc, 0x61a6000, v64
	v_cvt_pk_bf16_f32 v72, v34, v35
	v_cvt_pk_bf16_f32 v73, v36, v37
	v_cvt_pk_bf16_f32 v74, v38, v39
	v_cvt_pk_bf16_f32 v75, v40, v41
	v_addc_co_u32_e32 v77, vcc, 0, v65, vcc
	global_store_dwordx4 v[76:77], v[72:75], off
	s_cbranch_execz .LBB0_1295

; __device__ void phase_norm(const Params& p, int src_is_input, const bf16_t* delta, const float* gain, int final_out, int dry) {
;     ...
;     if (!final_out) {
;       ss2 = wave_sum(ss2);
;       if (lane == 0 && (!dry || ss2 < 0.f)) rstd[row] = rsqrtf(ss2 * (1.f / 1024.f) + 1e-6f);
;     }
;     row = nrow;
.LBB0_1298:
	s_andn2_b64 vcc, exec, s[10:11]
	s_cbranch_vccnz .LBB0_1286
	v_pk_mul_f32 v[34:35], v[34:35], v[34:35]
	v_pk_mul_f32 v[36:37], v[36:37], v[36:37]
	v_add_f32_e32 v0, v34, v35
	v_add_f32_e32 v0, v36, v0
	v_pk_mul_f32 v[38:39], v[38:39], v[38:39]
	v_add_f32_e32 v0, v37, v0
	v_add_f32_e32 v0, v38, v0
	v_pk_mul_f32 v[40:41], v[40:41], v[40:41]
	v_add_f32_e32 v0, v39, v0
	v_add_f32_e32 v0, v40, v0
	v_pk_mul_f32 v[42:43], v[42:43], v[42:43]
	v_add_f32_e32 v0, v41, v0
	v_add_f32_e32 v0, v42, v0
	v_pk_mul_f32 v[44:45], v[44:45], v[44:45]
	v_add_f32_e32 v0, v43, v0
	v_add_f32_e32 v0, v44, v0
	v_pk_mul_f32 v[46:47], v[46:47], v[46:47]
	v_add_f32_e32 v0, v45, v0
	v_add_f32_e32 v0, v46, v0
	v_pk_mul_f32 v[48:49], v[48:49], v[48:49]
	v_add_f32_e32 v0, v47, v0
	v_add_f32_e32 v0, v48, v0
	v_add_f32_e32 v0, v49, v0
	s_nop 1
	v_add_f32_dpp v0, v0, v0 quad_perm:[1,0,3,2] row_mask:0xf bank_mask:0xf
	s_nop 1
	v_add_f32_dpp v0, v0, v0 quad_perm:[2,3,0,1] row_mask:0xf bank_mask:0xf
	s_nop 1
	v_add_f32_dpp v0, v0, v0 row_ror:4 row_mask:0xf bank_mask:0xf
	s_nop 1
	v_add_f32_dpp v0, v0, v0 row_ror:8 row_mask:0xf bank_mask:0xf
	v_mov_b32_e32 v176, v0
	s_nop 1
	v_permlane16_swap_b32_e32 v0, v176
	s_nop 1
	v_add_f32_e32 v0, v0, v176
	v_mov_b32_e32 v176, v0
	s_nop 1
	v_permlane32_swap_b32_e32 v0, v176
	s_nop 1
	v_add_f32_e32 v0, v0, v176
	v_cmp_gt_f32_e32 vcc, 0, v0
	s_or_b64 s[26:27], s[22:23], vcc
	s_and_b64 s[30:31], s[4:5], s[26:27]
	s_and_saveexec_b64 s[26:27], s[30:31]
	s_cbranch_execz .LBB0_1285
	v_fmamk_f32 v0, v0, 0x3a800000, v216
	v_mul_f32_e32 v34, 0x4b800000, v0
	v_cmp_gt_f32_e32 vcc, s44, v0
	s_nop 1
	v_cndmask_b32_e32 v0, v0, v34, vcc
	v_rsq_f32_e32 v0, v0
	s_nop 0
	v_mul_f32_e32 v34, 0x45800000, v0
	v_cndmask_b32_e32 v0, v0, v34, vcc
	global_store_dword v[62:63], v0, off
	s_branch .LBB0_1285
.Lnrm_y_1285:
	s_or_b64 exec, exec, s[26:27]
.Lnrm_y_1286:
	s_and_b64 s[6:7], exec, s[6:7]
	s_or_b64 s[24:25], s[6:7], s[24:25]
	v_readlane_b32 s6, v254, 15
	v_readlane_b32 s7, v254, 16
	v_readlane_b32 s26, v254, 17
	v_readlane_b32 s27, v254, 18
	v_lshl_add_u64 v[54:55], v[54:55], 0, s[6:7]
	v_lshl_add_u64 v[56:57], v[56:57], 0, s[6:7]
	v_lshl_add_u64 v[60:61], v[60:61], 0, s[6:7]
	v_readlane_b32 s6, v254, 21
	v_readlane_b32 s7, v254, 22
	v_lshl_add_u64 v[58:59], v[58:59], 0, s[26:27]
	v_mov_b64_e32 v[38:39], v[188:189]
	v_lshl_add_u64 v[62:63], v[62:63], 0, s[6:7]
	v_mov_b64_e32 v[40:41], v[190:191]
	v_mov_b64_e32 v[34:35], v[192:193]
	v_mov_b64_e32 v[36:37], v[194:195]
	v_mov_b64_e32 v[46:47], v[180:181]
	v_mov_b64_e32 v[48:49], v[182:183]
	v_mov_b64_e32 v[42:43], v[184:185]
	v_mov_b64_e32 v[44:45], v[186:187]
	s_andn2_b64 exec, exec, s[24:25]
	s_cbranch_execz .LBB0_1280
	s_branch .LBB0_1287

; __device__ void phase_norm(const Params& p, int src_is_input, const bf16_t* delta, const float* gain, int final_out, int dry) {
;     ...
;     if (nrow < T_TOK) NORM_FETCH(nrow);
.Lnrm_ld_y:
	v_lshl_add_u64 v[18:19], v[56:57], 0, v[52:53]
	v_add_co_u32_e32 v30, vcc, 0x61a6000, v18
	v_lshl_add_u64 v[22:23], v[60:61], 0, v[52:53]
	s_nop 0
	v_addc_co_u32_e32 v31, vcc, 0, v19, vcc
	global_load_dwordx4 v[18:21], v[22:23], off
	s_nop 0
	global_load_dwordx4 v[22:25], v[22:23], off offset:1024
	s_nop 0
	global_load_dwordx4 v[26:29], v[30:31], off
	s_nop 0
	global_load_dwordx4 v[30:33], v[30:31], off offset:1024
